# router cross-row reduction via DPP lane packing + permlane16/32 swaps (order-preserving), results placed with v_writelane; compare/cndmask/readlane round trips removed
# speedup vs baseline: 1.0346x; 1.0061x over previous
; DEVI float wave_sum(float v) {
;   v = dpp_add_(v, 0);
;   v = dpp_add_(v, 1);
;   v = dpp_add_(v, 2);
;   v = dpp_add_(v, 3);
;   const int iv = __float_as_int(v);
;   const float r0 = __int_as_float(__builtin_amdgcn_readlane(iv, 0)), r1 = __int_as_float(__builtin_amdgcn_readlane(iv, 16));
;   const float r2 = __int_as_float(__builtin_amdgcn_readlane(iv, 32)), r3 = __int_as_float(__builtin_amdgcn_readlane(iv, 48));
;   return (r0 + r1) + (r2 + r3);
; DEVI void phase_p7(const int TIDX, const int BIDX, const int GDIM, KAP KA, unsigned char* WSB, float* OUTB, int l, unsigned char* smem) {
;     ...
; #pragma unroll 4
;       for (int c = 0; c < 36; ++c) {
;         float4 wv[4];
; #pragma unroll
;         for (int j = 0; j < 4; ++j) wv[j] = *(const float4*)(WR + c * 1024 + j * 256 + lane * 4);
; #pragma unroll
;         for (int t = 0; t < 4; ++t) {
;           float s = 0.f;
; #pragma unroll
;           for (int j = 0; j < 4; ++j) s += v[t][j].x * wv[j].x + v[t][j].y * wv[j].y + v[t][j].z * wv[j].z + v[t][j].w * wv[j].w;
;           s = wave_sum(s);
;           if (lane == c) mine[t] = s;
;         }
;       }
.LBB0_69:
	v_lshl_add_u64 v[80:81], v[42:43], 0, s[0:1]
	s_mov_b64 s[24:25], 0x2221000
	s_mov_b64 s[26:27], 0x2223000
	v_lshl_add_u64 v[90:91], v[80:81], 0, s[24:25]
	v_lshl_add_u64 v[92:93], v[80:81], 0, s[26:27]
	global_load_dwordx4 v[142:145], v[90:91], off offset:-4096
	global_load_dwordx4 v[146:149], v[90:91], off offset:-3072
	global_load_dwordx4 v[150:153], v[90:91], off offset:-2048
	global_load_dwordx4 v[154:157], v[90:91], off offset:-1024
	global_load_dwordx4 v[162:165], v[90:91], off
	global_load_dwordx4 v[166:169], v[90:91], off offset:1024
	global_load_dwordx4 v[170:173], v[90:91], off offset:2048
	global_load_dwordx4 v[174:177], v[90:91], off offset:3072
	global_load_dwordx4 v[178:181], v[92:93], off offset:-4096
	global_load_dwordx4 v[182:185], v[92:93], off offset:-3072
	global_load_dwordx4 v[186:189], v[92:93], off offset:-2048
	global_load_dwordx4 v[190:193], v[92:93], off offset:-1024
	global_load_dwordx4 v[196:199], v[92:93], off
	global_load_dwordx4 v[200:203], v[92:93], off offset:1024
	global_load_dwordx4 v[236:239], v[92:93], off offset:2048
	global_load_dwordx4 v[240:243], v[92:93], off offset:3072
	s_waitcnt vmcnt(14)
	v_mov_b32_e32 v252, v142
	v_mov_b32_e32 v253, v146
	v_mov_b32_e32 v146, v143
	v_mov_b32_e32 v158, v144
	v_mov_b32_e32 v159, v148
	v_mov_b32_e32 v148, v145
	v_pk_mul_f32 v[244:245], v[26:27], v[146:147]
	v_pk_mul_f32 v[246:247], v[56:57], v[146:147]
	v_pk_mul_f32 v[248:249], v[4:5], v[146:147]
	v_pk_mul_f32 v[250:251], v[20:21], v[146:147]
	v_pk_fma_f32 v[244:245], v[24:25], v[252:253], v[244:245]
	v_pk_fma_f32 v[246:247], v[54:55], v[252:253], v[246:247]
	v_pk_fma_f32 v[248:249], v[16:17], v[252:253], v[248:249]
	v_pk_fma_f32 v[250:251], v[14:15], v[252:253], v[250:251]
	v_pk_fma_f32 v[244:245], v[28:29], v[158:159], v[244:245]
	v_pk_fma_f32 v[246:247], v[58:59], v[158:159], v[246:247]
	v_pk_fma_f32 v[248:249], v[18:19], v[158:159], v[248:249]
	v_pk_fma_f32 v[250:251], v[22:23], v[158:159], v[250:251]
	v_pk_fma_f32 v[244:245], v[30:31], v[148:149], v[244:245]
	v_pk_fma_f32 v[246:247], v[60:61], v[148:149], v[246:247]
	v_pk_fma_f32 v[248:249], v[2:3], v[148:149], v[248:249]
	v_pk_fma_f32 v[250:251], v[70:71], v[148:149], v[250:251]
	v_add_f32_e32 v160, 0, v244
	v_add_f32_e32 v194, 0, v246
	v_add_f32_e32 v231, 0, v248
	v_add_f32_e32 v232, 0, v250
	v_add_f32_e32 v160, v160, v245
	v_add_f32_e32 v194, v194, v247
	v_add_f32_e32 v231, v231, v249
	v_add_f32_e32 v232, v232, v251
	s_waitcnt vmcnt(12)
	v_mov_b32_e32 v252, v150
	v_mov_b32_e32 v253, v154
	v_mov_b32_e32 v154, v151
	v_mov_b32_e32 v158, v152
	v_mov_b32_e32 v159, v156
	v_mov_b32_e32 v156, v153
	v_pk_mul_f32 v[244:245], v[48:49], v[154:155]
	v_pk_mul_f32 v[246:247], v[64:65], v[154:155]
	v_pk_mul_f32 v[248:249], v[8:9], v[154:155]
	v_pk_mul_f32 v[250:251], v[74:75], v[154:155]
	v_pk_fma_f32 v[244:245], v[46:47], v[252:253], v[244:245]
	v_pk_fma_f32 v[246:247], v[62:63], v[252:253], v[246:247]
	v_pk_fma_f32 v[248:249], v[6:7], v[252:253], v[248:249]
	v_pk_fma_f32 v[250:251], v[72:73], v[252:253], v[250:251]
	v_pk_fma_f32 v[244:245], v[50:51], v[158:159], v[244:245]
	v_pk_fma_f32 v[246:247], v[66:67], v[158:159], v[246:247]
	v_pk_fma_f32 v[248:249], v[12:13], v[158:159], v[248:249]
	v_pk_fma_f32 v[250:251], v[76:77], v[158:159], v[250:251]
	v_pk_fma_f32 v[244:245], v[52:53], v[156:157], v[244:245]
	v_pk_fma_f32 v[246:247], v[68:69], v[156:157], v[246:247]
	v_pk_fma_f32 v[248:249], v[10:11], v[156:157], v[248:249]
	v_pk_fma_f32 v[250:251], v[78:79], v[156:157], v[250:251]
	v_add_f32_e32 v160, v160, v244
	v_add_f32_e32 v194, v194, v246
	v_add_f32_e32 v231, v231, v248
	v_add_f32_e32 v232, v232, v250
	v_add_f32_e32 v160, v160, v245
	v_add_f32_e32 v194, v194, v247
	v_add_f32_e32 v231, v231, v249
	v_add_f32_e32 v232, v232, v251
	s_mov_b32 m0, s2
	v_add_f32_dpp v160, v160, v160 quad_perm:[1,0,3,2] row_mask:0xf bank_mask:0xf bound_ctrl:1
	v_add_f32_dpp v194, v194, v194 quad_perm:[1,0,3,2] row_mask:0xf bank_mask:0xf bound_ctrl:1
	v_add_f32_dpp v231, v231, v231 quad_perm:[1,0,3,2] row_mask:0xf bank_mask:0xf bound_ctrl:1
	v_add_f32_dpp v232, v232, v232 quad_perm:[1,0,3,2] row_mask:0xf bank_mask:0xf bound_ctrl:1
	v_add_f32_dpp v160, v160, v160 quad_perm:[2,3,0,1] row_mask:0xf bank_mask:0xf bound_ctrl:1
	v_add_f32_dpp v194, v194, v194 quad_perm:[2,3,0,1] row_mask:0xf bank_mask:0xf bound_ctrl:1
	v_add_f32_dpp v231, v231, v231 quad_perm:[2,3,0,1] row_mask:0xf bank_mask:0xf bound_ctrl:1
	v_add_f32_dpp v232, v232, v232 quad_perm:[2,3,0,1] row_mask:0xf bank_mask:0xf bound_ctrl:1
	v_add_f32_dpp v160, v160, v160 row_half_mirror row_mask:0xf bank_mask:0xf bound_ctrl:1
	v_add_f32_dpp v194, v194, v194 row_half_mirror row_mask:0xf bank_mask:0xf bound_ctrl:1
	v_add_f32_dpp v231, v231, v231 row_half_mirror row_mask:0xf bank_mask:0xf bound_ctrl:1
	v_add_f32_dpp v232, v232, v232 row_half_mirror row_mask:0xf bank_mask:0xf bound_ctrl:1
	v_add_f32_dpp v160, v160, v160 row_mirror row_mask:0xf bank_mask:0xf bound_ctrl:1
	v_add_f32_dpp v194, v194, v194 row_mirror row_mask:0xf bank_mask:0xf bound_ctrl:1
	v_add_f32_dpp v231, v231, v231 row_mirror row_mask:0xf bank_mask:0xf bound_ctrl:1
	v_add_f32_dpp v232, v232, v232 row_mirror row_mask:0xf bank_mask:0xf bound_ctrl:1
	v_mov_b32_e32 v94, v160
	s_waitcnt vmcnt(10)
; DEVI float wave_sum(float v) {
;   v = dpp_add_(v, 0);
;   v = dpp_add_(v, 1);
;   v = dpp_add_(v, 2);
;   v = dpp_add_(v, 3);
;   const int iv = __float_as_int(v);
;   const float r0 = __int_as_float(__builtin_amdgcn_readlane(iv, 0)), r1 = __int_as_float(__builtin_amdgcn_readlane(iv, 16));
;   const float r2 = __int_as_float(__builtin_amdgcn_readlane(iv, 32)), r3 = __int_as_float(__builtin_amdgcn_readlane(iv, 48));
;   return (r0 + r1) + (r2 + r3);
; DEVI void phase_p7(const int TIDX, const int BIDX, const int GDIM, KAP KA, unsigned char* WSB, float* OUTB, int l, unsigned char* smem) {
;     ...
; #pragma unroll 4
;       for (int c = 0; c < 36; ++c) {
;         float4 wv[4];
; #pragma unroll
;         for (int j = 0; j < 4; ++j) wv[j] = *(const float4*)(WR + c * 1024 + j * 256 + lane * 4);
; #pragma unroll
;         for (int t = 0; t < 4; ++t) {
;           float s = 0.f;
; #pragma unroll
;           for (int j = 0; j < 4; ++j) s += v[t][j].x * wv[j].x + v[t][j].y * wv[j].y + v[t][j].z * wv[j].z + v[t][j].w * wv[j].w;
;           s = wave_sum(s);
;           if (lane == c) mine[t] = s;
;         }
;       }
	v_mov_b32_e32 v252, v162
	v_mov_b32_dpp v94, v194 row_shr:4 row_mask:0xf bank_mask:0x2
	v_mov_b32_e32 v253, v166
	v_mov_b32_e32 v166, v163
	v_mov_b32_dpp v94, v231 row_shr:8 row_mask:0xf bank_mask:0x4
	v_mov_b32_e32 v158, v164
	v_mov_b32_e32 v159, v168
	v_mov_b32_dpp v94, v232 row_shr:12 row_mask:0xf bank_mask:0x8
	v_mov_b32_e32 v95, v94
	v_mov_b32_e32 v168, v165
	v_pk_mul_f32 v[244:245], v[26:27], v[166:167]
	v_permlane16_swap_b32_e32 v94, v95
	v_pk_mul_f32 v[246:247], v[56:57], v[166:167]
	v_add_f32_e32 v96, v94, v95
	v_mov_b32_e32 v97, v96
	v_pk_mul_f32 v[248:249], v[4:5], v[166:167]
	v_pk_mul_f32 v[250:251], v[20:21], v[166:167]
	v_permlane32_swap_b32_e32 v96, v97
	v_pk_fma_f32 v[244:245], v[24:25], v[252:253], v[244:245]
	v_add_f32_e32 v98, v96, v97
	v_pk_fma_f32 v[246:247], v[54:55], v[252:253], v[246:247]
	v_readlane_b32 s24, v98, 0
	v_readlane_b32 s25, v98, 4
	v_readlane_b32 s26, v98, 8
	v_readlane_b32 s27, v98, 12
	v_writelane_b32 v82, s24, m0
	v_writelane_b32 v33, s25, m0
	v_writelane_b32 v0, s26, m0
	v_writelane_b32 v1, s27, m0
	v_pk_fma_f32 v[248:249], v[16:17], v[252:253], v[248:249]
	v_pk_fma_f32 v[250:251], v[14:15], v[252:253], v[250:251]
	v_pk_fma_f32 v[244:245], v[28:29], v[158:159], v[244:245]
	v_pk_fma_f32 v[246:247], v[58:59], v[158:159], v[246:247]
	v_pk_fma_f32 v[248:249], v[18:19], v[158:159], v[248:249]
	v_pk_fma_f32 v[250:251], v[22:23], v[158:159], v[250:251]
	v_pk_fma_f32 v[244:245], v[30:31], v[168:169], v[244:245]
	v_pk_fma_f32 v[246:247], v[60:61], v[168:169], v[246:247]
	v_pk_fma_f32 v[248:249], v[2:3], v[168:169], v[248:249]
	v_pk_fma_f32 v[250:251], v[70:71], v[168:169], v[250:251]
	v_add_f32_e32 v160, 0, v244
	v_add_f32_e32 v194, 0, v246
	v_add_f32_e32 v231, 0, v248
	v_add_f32_e32 v232, 0, v250
	v_add_f32_e32 v160, v160, v245
	v_add_f32_e32 v194, v194, v247
	v_add_f32_e32 v231, v231, v249
	v_add_f32_e32 v232, v232, v251
	s_waitcnt vmcnt(8)
	v_mov_b32_e32 v252, v170
	v_mov_b32_e32 v253, v174
	v_mov_b32_e32 v174, v171
	v_mov_b32_e32 v158, v172
	v_mov_b32_e32 v159, v176
	v_mov_b32_e32 v176, v173
	v_pk_mul_f32 v[244:245], v[48:49], v[174:175]
	v_pk_mul_f32 v[246:247], v[64:65], v[174:175]
	v_pk_mul_f32 v[248:249], v[8:9], v[174:175]
	v_pk_mul_f32 v[250:251], v[74:75], v[174:175]
	v_pk_fma_f32 v[244:245], v[46:47], v[252:253], v[244:245]
	v_pk_fma_f32 v[246:247], v[62:63], v[252:253], v[246:247]
	v_pk_fma_f32 v[248:249], v[6:7], v[252:253], v[248:249]
	v_pk_fma_f32 v[250:251], v[72:73], v[252:253], v[250:251]
	v_pk_fma_f32 v[244:245], v[50:51], v[158:159], v[244:245]
	v_pk_fma_f32 v[246:247], v[66:67], v[158:159], v[246:247]
	v_pk_fma_f32 v[248:249], v[12:13], v[158:159], v[248:249]
	v_pk_fma_f32 v[250:251], v[76:77], v[158:159], v[250:251]
	v_pk_fma_f32 v[244:245], v[52:53], v[176:177], v[244:245]
	v_pk_fma_f32 v[246:247], v[68:69], v[176:177], v[246:247]
	v_pk_fma_f32 v[248:249], v[10:11], v[176:177], v[248:249]
	v_pk_fma_f32 v[250:251], v[78:79], v[176:177], v[250:251]
	v_add_f32_e32 v160, v160, v244
	v_add_f32_e32 v194, v194, v246
	v_add_f32_e32 v231, v231, v248
	v_add_f32_e32 v232, v232, v250
	v_add_f32_e32 v160, v160, v245
	v_add_f32_e32 v194, v194, v247
	v_add_f32_e32 v231, v231, v249
	v_add_f32_e32 v232, v232, v251
	s_or_b32 s101, s2, 1
	s_mov_b32 m0, s101
	v_add_f32_dpp v160, v160, v160 quad_perm:[1,0,3,2] row_mask:0xf bank_mask:0xf bound_ctrl:1
	v_add_f32_dpp v194, v194, v194 quad_perm:[1,0,3,2] row_mask:0xf bank_mask:0xf bound_ctrl:1
	v_add_f32_dpp v231, v231, v231 quad_perm:[1,0,3,2] row_mask:0xf bank_mask:0xf bound_ctrl:1
	v_add_f32_dpp v232, v232, v232 quad_perm:[1,0,3,2] row_mask:0xf bank_mask:0xf bound_ctrl:1
	v_add_f32_dpp v160, v160, v160 quad_perm:[2,3,0,1] row_mask:0xf bank_mask:0xf bound_ctrl:1
	v_add_f32_dpp v194, v194, v194 quad_perm:[2,3,0,1] row_mask:0xf bank_mask:0xf bound_ctrl:1
	v_add_f32_dpp v231, v231, v231 quad_perm:[2,3,0,1] row_mask:0xf bank_mask:0xf bound_ctrl:1
	v_add_f32_dpp v232, v232, v232 quad_perm:[2,3,0,1] row_mask:0xf bank_mask:0xf bound_ctrl:1
	v_add_f32_dpp v160, v160, v160 row_half_mirror row_mask:0xf bank_mask:0xf bound_ctrl:1
	v_add_f32_dpp v194, v194, v194 row_half_mirror row_mask:0xf bank_mask:0xf bound_ctrl:1
	v_add_f32_dpp v231, v231, v231 row_half_mirror row_mask:0xf bank_mask:0xf bound_ctrl:1
	v_add_f32_dpp v232, v232, v232 row_half_mirror row_mask:0xf bank_mask:0xf bound_ctrl:1
	v_add_f32_dpp v160, v160, v160 row_mirror row_mask:0xf bank_mask:0xf bound_ctrl:1
	v_add_f32_dpp v194, v194, v194 row_mirror row_mask:0xf bank_mask:0xf bound_ctrl:1
	v_add_f32_dpp v231, v231, v231 row_mirror row_mask:0xf bank_mask:0xf bound_ctrl:1
	v_add_f32_dpp v232, v232, v232 row_mirror row_mask:0xf bank_mask:0xf bound_ctrl:1
	v_mov_b32_e32 v94, v160
	s_waitcnt vmcnt(6)
; DEVI float wave_sum(float v) {
;   v = dpp_add_(v, 0);
;   v = dpp_add_(v, 1);
;   v = dpp_add_(v, 2);
;   v = dpp_add_(v, 3);
;   const int iv = __float_as_int(v);
;   const float r0 = __int_as_float(__builtin_amdgcn_readlane(iv, 0)), r1 = __int_as_float(__builtin_amdgcn_readlane(iv, 16));
;   const float r2 = __int_as_float(__builtin_amdgcn_readlane(iv, 32)), r3 = __int_as_float(__builtin_amdgcn_readlane(iv, 48));
;   return (r0 + r1) + (r2 + r3);
; DEVI void phase_p7(const int TIDX, const int BIDX, const int GDIM, KAP KA, unsigned char* WSB, float* OUTB, int l, unsigned char* smem) {
;     ...
; #pragma unroll 4
;       for (int c = 0; c < 36; ++c) {
;         float4 wv[4];
; #pragma unroll
;         for (int j = 0; j < 4; ++j) wv[j] = *(const float4*)(WR + c * 1024 + j * 256 + lane * 4);
; #pragma unroll
;         for (int t = 0; t < 4; ++t) {
;           float s = 0.f;
; #pragma unroll
;           for (int j = 0; j < 4; ++j) s += v[t][j].x * wv[j].x + v[t][j].y * wv[j].y + v[t][j].z * wv[j].z + v[t][j].w * wv[j].w;
;           s = wave_sum(s);
;           if (lane == c) mine[t] = s;
;         }
;       }
	v_mov_b32_e32 v252, v178
	v_mov_b32_dpp v94, v194 row_shr:4 row_mask:0xf bank_mask:0x2
	v_mov_b32_e32 v253, v182
	v_mov_b32_e32 v182, v179
	v_mov_b32_dpp v94, v231 row_shr:8 row_mask:0xf bank_mask:0x4
	v_mov_b32_e32 v158, v180
	v_mov_b32_e32 v159, v184
	v_mov_b32_dpp v94, v232 row_shr:12 row_mask:0xf bank_mask:0x8
	v_mov_b32_e32 v95, v94
	v_mov_b32_e32 v184, v181
	v_pk_mul_f32 v[244:245], v[26:27], v[182:183]
	v_permlane16_swap_b32_e32 v94, v95
	v_pk_mul_f32 v[246:247], v[56:57], v[182:183]
	v_add_f32_e32 v96, v94, v95
	v_mov_b32_e32 v97, v96
	v_pk_mul_f32 v[248:249], v[4:5], v[182:183]
	v_pk_mul_f32 v[250:251], v[20:21], v[182:183]
	v_permlane32_swap_b32_e32 v96, v97
	v_pk_fma_f32 v[244:245], v[24:25], v[252:253], v[244:245]
	v_add_f32_e32 v98, v96, v97
	v_pk_fma_f32 v[246:247], v[54:55], v[252:253], v[246:247]
	v_readlane_b32 s24, v98, 0
	v_readlane_b32 s25, v98, 4
	v_readlane_b32 s26, v98, 8
	v_readlane_b32 s27, v98, 12
	v_writelane_b32 v82, s24, m0
	v_writelane_b32 v33, s25, m0
	v_writelane_b32 v0, s26, m0
	v_writelane_b32 v1, s27, m0
	v_pk_fma_f32 v[248:249], v[16:17], v[252:253], v[248:249]
	v_pk_fma_f32 v[250:251], v[14:15], v[252:253], v[250:251]
	v_pk_fma_f32 v[244:245], v[28:29], v[158:159], v[244:245]
	v_pk_fma_f32 v[246:247], v[58:59], v[158:159], v[246:247]
	v_pk_fma_f32 v[248:249], v[18:19], v[158:159], v[248:249]
	v_pk_fma_f32 v[250:251], v[22:23], v[158:159], v[250:251]
	v_pk_fma_f32 v[244:245], v[30:31], v[184:185], v[244:245]
	v_pk_fma_f32 v[246:247], v[60:61], v[184:185], v[246:247]
	v_pk_fma_f32 v[248:249], v[2:3], v[184:185], v[248:249]
	v_pk_fma_f32 v[250:251], v[70:71], v[184:185], v[250:251]
	v_add_f32_e32 v160, 0, v244
	v_add_f32_e32 v194, 0, v246
	v_add_f32_e32 v231, 0, v248
	v_add_f32_e32 v232, 0, v250
	v_add_f32_e32 v160, v160, v245
	v_add_f32_e32 v194, v194, v247
	v_add_f32_e32 v231, v231, v249
	v_add_f32_e32 v232, v232, v251
	s_waitcnt vmcnt(4)
	v_mov_b32_e32 v252, v186
	v_mov_b32_e32 v253, v190
	v_mov_b32_e32 v190, v187
	v_mov_b32_e32 v158, v188
	v_mov_b32_e32 v159, v192
	v_mov_b32_e32 v192, v189
	v_pk_mul_f32 v[244:245], v[48:49], v[190:191]
	v_pk_mul_f32 v[246:247], v[64:65], v[190:191]
	v_pk_mul_f32 v[248:249], v[8:9], v[190:191]
	v_pk_mul_f32 v[250:251], v[74:75], v[190:191]
	v_pk_fma_f32 v[244:245], v[46:47], v[252:253], v[244:245]
	v_pk_fma_f32 v[246:247], v[62:63], v[252:253], v[246:247]
	v_pk_fma_f32 v[248:249], v[6:7], v[252:253], v[248:249]
	v_pk_fma_f32 v[250:251], v[72:73], v[252:253], v[250:251]
	v_pk_fma_f32 v[244:245], v[50:51], v[158:159], v[244:245]
	v_pk_fma_f32 v[246:247], v[66:67], v[158:159], v[246:247]
	v_pk_fma_f32 v[248:249], v[12:13], v[158:159], v[248:249]
	v_pk_fma_f32 v[250:251], v[76:77], v[158:159], v[250:251]
	v_pk_fma_f32 v[244:245], v[52:53], v[192:193], v[244:245]
	v_pk_fma_f32 v[246:247], v[68:69], v[192:193], v[246:247]
	v_pk_fma_f32 v[248:249], v[10:11], v[192:193], v[248:249]
	v_pk_fma_f32 v[250:251], v[78:79], v[192:193], v[250:251]
	v_add_f32_e32 v160, v160, v244
	v_add_f32_e32 v194, v194, v246
	v_add_f32_e32 v231, v231, v248
	v_add_f32_e32 v232, v232, v250
	v_add_f32_e32 v160, v160, v245
	v_add_f32_e32 v194, v194, v247
	v_add_f32_e32 v231, v231, v249
	v_add_f32_e32 v232, v232, v251
	s_or_b32 s101, s2, 2
	s_mov_b32 m0, s101
	v_add_f32_dpp v160, v160, v160 quad_perm:[1,0,3,2] row_mask:0xf bank_mask:0xf bound_ctrl:1
	v_add_f32_dpp v194, v194, v194 quad_perm:[1,0,3,2] row_mask:0xf bank_mask:0xf bound_ctrl:1
	v_add_f32_dpp v231, v231, v231 quad_perm:[1,0,3,2] row_mask:0xf bank_mask:0xf bound_ctrl:1
	v_add_f32_dpp v232, v232, v232 quad_perm:[1,0,3,2] row_mask:0xf bank_mask:0xf bound_ctrl:1
	v_add_f32_dpp v160, v160, v160 quad_perm:[2,3,0,1] row_mask:0xf bank_mask:0xf bound_ctrl:1
	v_add_f32_dpp v194, v194, v194 quad_perm:[2,3,0,1] row_mask:0xf bank_mask:0xf bound_ctrl:1
	v_add_f32_dpp v231, v231, v231 quad_perm:[2,3,0,1] row_mask:0xf bank_mask:0xf bound_ctrl:1
	v_add_f32_dpp v232, v232, v232 quad_perm:[2,3,0,1] row_mask:0xf bank_mask:0xf bound_ctrl:1
	v_add_f32_dpp v160, v160, v160 row_half_mirror row_mask:0xf bank_mask:0xf bound_ctrl:1
	v_add_f32_dpp v194, v194, v194 row_half_mirror row_mask:0xf bank_mask:0xf bound_ctrl:1
	v_add_f32_dpp v231, v231, v231 row_half_mirror row_mask:0xf bank_mask:0xf bound_ctrl:1
	v_add_f32_dpp v232, v232, v232 row_half_mirror row_mask:0xf bank_mask:0xf bound_ctrl:1
	v_add_f32_dpp v160, v160, v160 row_mirror row_mask:0xf bank_mask:0xf bound_ctrl:1
	v_add_f32_dpp v194, v194, v194 row_mirror row_mask:0xf bank_mask:0xf bound_ctrl:1
	v_add_f32_dpp v231, v231, v231 row_mirror row_mask:0xf bank_mask:0xf bound_ctrl:1
	v_add_f32_dpp v232, v232, v232 row_mirror row_mask:0xf bank_mask:0xf bound_ctrl:1
	v_mov_b32_e32 v94, v160
	s_waitcnt vmcnt(2)
; DEVI float wave_sum(float v) {
;   v = dpp_add_(v, 0);
;   v = dpp_add_(v, 1);
;   v = dpp_add_(v, 2);
;   v = dpp_add_(v, 3);
;   const int iv = __float_as_int(v);
;   const float r0 = __int_as_float(__builtin_amdgcn_readlane(iv, 0)), r1 = __int_as_float(__builtin_amdgcn_readlane(iv, 16));
;   const float r2 = __int_as_float(__builtin_amdgcn_readlane(iv, 32)), r3 = __int_as_float(__builtin_amdgcn_readlane(iv, 48));
;   return (r0 + r1) + (r2 + r3);
; DEVI void phase_p7(const int TIDX, const int BIDX, const int GDIM, KAP KA, unsigned char* WSB, float* OUTB, int l, unsigned char* smem) {
;     ...
; #pragma unroll 4
;       for (int c = 0; c < 36; ++c) {
;         float4 wv[4];
; #pragma unroll
;         for (int j = 0; j < 4; ++j) wv[j] = *(const float4*)(WR + c * 1024 + j * 256 + lane * 4);
; #pragma unroll
;         for (int t = 0; t < 4; ++t) {
;           float s = 0.f;
; #pragma unroll
;           for (int j = 0; j < 4; ++j) s += v[t][j].x * wv[j].x + v[t][j].y * wv[j].y + v[t][j].z * wv[j].z + v[t][j].w * wv[j].w;
;           s = wave_sum(s);
;           if (lane == c) mine[t] = s;
;         }
;       }
	v_mov_b32_e32 v252, v196
	v_mov_b32_dpp v94, v194 row_shr:4 row_mask:0xf bank_mask:0x2
	v_mov_b32_e32 v253, v200
	v_mov_b32_e32 v200, v197
	v_mov_b32_dpp v94, v231 row_shr:8 row_mask:0xf bank_mask:0x4
	v_mov_b32_e32 v158, v198
	v_mov_b32_e32 v159, v202
	v_mov_b32_dpp v94, v232 row_shr:12 row_mask:0xf bank_mask:0x8
	v_mov_b32_e32 v95, v94
	v_mov_b32_e32 v202, v199
	v_pk_mul_f32 v[244:245], v[26:27], v[200:201]
	v_permlane16_swap_b32_e32 v94, v95
	v_pk_mul_f32 v[246:247], v[56:57], v[200:201]
	v_add_f32_e32 v96, v94, v95
	v_mov_b32_e32 v97, v96
	v_pk_mul_f32 v[248:249], v[4:5], v[200:201]
	v_pk_mul_f32 v[250:251], v[20:21], v[200:201]
	v_permlane32_swap_b32_e32 v96, v97
	v_pk_fma_f32 v[244:245], v[24:25], v[252:253], v[244:245]
	v_add_f32_e32 v98, v96, v97
	v_pk_fma_f32 v[246:247], v[54:55], v[252:253], v[246:247]
	v_readlane_b32 s24, v98, 0
	v_readlane_b32 s25, v98, 4
	v_readlane_b32 s26, v98, 8
	v_readlane_b32 s27, v98, 12
	v_writelane_b32 v82, s24, m0
	v_writelane_b32 v33, s25, m0
	v_writelane_b32 v0, s26, m0
	v_writelane_b32 v1, s27, m0
	v_pk_fma_f32 v[248:249], v[16:17], v[252:253], v[248:249]
	v_pk_fma_f32 v[250:251], v[14:15], v[252:253], v[250:251]
	v_pk_fma_f32 v[244:245], v[28:29], v[158:159], v[244:245]
	v_pk_fma_f32 v[246:247], v[58:59], v[158:159], v[246:247]
	v_pk_fma_f32 v[248:249], v[18:19], v[158:159], v[248:249]
	v_pk_fma_f32 v[250:251], v[22:23], v[158:159], v[250:251]
	v_pk_fma_f32 v[244:245], v[30:31], v[202:203], v[244:245]
	v_pk_fma_f32 v[246:247], v[60:61], v[202:203], v[246:247]
	v_pk_fma_f32 v[248:249], v[2:3], v[202:203], v[248:249]
	v_pk_fma_f32 v[250:251], v[70:71], v[202:203], v[250:251]
	v_add_f32_e32 v160, 0, v244
	v_add_f32_e32 v194, 0, v246
	v_add_f32_e32 v231, 0, v248
	v_add_f32_e32 v232, 0, v250
	v_add_f32_e32 v160, v160, v245
	v_add_f32_e32 v194, v194, v247
	v_add_f32_e32 v231, v231, v249
	v_add_f32_e32 v232, v232, v251
	s_waitcnt vmcnt(0)
	v_mov_b32_e32 v252, v236
	v_mov_b32_e32 v253, v240
	v_mov_b32_e32 v240, v237
	v_mov_b32_e32 v158, v238
	v_mov_b32_e32 v159, v242
	v_mov_b32_e32 v242, v239
	v_pk_mul_f32 v[244:245], v[48:49], v[240:241]
	v_pk_mul_f32 v[246:247], v[64:65], v[240:241]
	v_pk_mul_f32 v[248:249], v[8:9], v[240:241]
	v_pk_mul_f32 v[250:251], v[74:75], v[240:241]
	v_pk_fma_f32 v[244:245], v[46:47], v[252:253], v[244:245]
	v_pk_fma_f32 v[246:247], v[62:63], v[252:253], v[246:247]
	v_pk_fma_f32 v[248:249], v[6:7], v[252:253], v[248:249]
	v_pk_fma_f32 v[250:251], v[72:73], v[252:253], v[250:251]
	v_pk_fma_f32 v[244:245], v[50:51], v[158:159], v[244:245]
	v_pk_fma_f32 v[246:247], v[66:67], v[158:159], v[246:247]
	v_pk_fma_f32 v[248:249], v[12:13], v[158:159], v[248:249]
	v_pk_fma_f32 v[250:251], v[76:77], v[158:159], v[250:251]
	v_pk_fma_f32 v[244:245], v[52:53], v[242:243], v[244:245]
	v_pk_fma_f32 v[246:247], v[68:69], v[242:243], v[246:247]
	v_pk_fma_f32 v[248:249], v[10:11], v[242:243], v[248:249]
	v_pk_fma_f32 v[250:251], v[78:79], v[242:243], v[250:251]
	v_add_f32_e32 v160, v160, v244
	v_add_f32_e32 v194, v194, v246
	v_add_f32_e32 v231, v231, v248
	v_add_f32_e32 v232, v232, v250
	v_add_f32_e32 v160, v160, v245
	v_add_f32_e32 v194, v194, v247
	v_add_f32_e32 v231, v231, v249
	v_add_f32_e32 v232, v232, v251
	s_or_b32 s101, s2, 3
	s_mov_b32 m0, s101
	v_add_f32_dpp v160, v160, v160 quad_perm:[1,0,3,2] row_mask:0xf bank_mask:0xf bound_ctrl:1
	v_add_f32_dpp v194, v194, v194 quad_perm:[1,0,3,2] row_mask:0xf bank_mask:0xf bound_ctrl:1
	v_add_f32_dpp v231, v231, v231 quad_perm:[1,0,3,2] row_mask:0xf bank_mask:0xf bound_ctrl:1
	v_add_f32_dpp v232, v232, v232 quad_perm:[1,0,3,2] row_mask:0xf bank_mask:0xf bound_ctrl:1
	v_add_f32_dpp v160, v160, v160 quad_perm:[2,3,0,1] row_mask:0xf bank_mask:0xf bound_ctrl:1
	v_add_f32_dpp v194, v194, v194 quad_perm:[2,3,0,1] row_mask:0xf bank_mask:0xf bound_ctrl:1
	v_add_f32_dpp v231, v231, v231 quad_perm:[2,3,0,1] row_mask:0xf bank_mask:0xf bound_ctrl:1
	v_add_f32_dpp v232, v232, v232 quad_perm:[2,3,0,1] row_mask:0xf bank_mask:0xf bound_ctrl:1
	v_add_f32_dpp v160, v160, v160 row_half_mirror row_mask:0xf bank_mask:0xf bound_ctrl:1
	v_add_f32_dpp v194, v194, v194 row_half_mirror row_mask:0xf bank_mask:0xf bound_ctrl:1
	v_add_f32_dpp v231, v231, v231 row_half_mirror row_mask:0xf bank_mask:0xf bound_ctrl:1
	v_add_f32_dpp v232, v232, v232 row_half_mirror row_mask:0xf bank_mask:0xf bound_ctrl:1
	v_add_f32_dpp v160, v160, v160 row_mirror row_mask:0xf bank_mask:0xf bound_ctrl:1
	v_add_f32_dpp v194, v194, v194 row_mirror row_mask:0xf bank_mask:0xf bound_ctrl:1
	v_add_f32_dpp v231, v231, v231 row_mirror row_mask:0xf bank_mask:0xf bound_ctrl:1
	v_add_f32_dpp v232, v232, v232 row_mirror row_mask:0xf bank_mask:0xf bound_ctrl:1
	v_mov_b32_e32 v94, v160
	s_add_i32 s2, s2, 4
	s_add_u32 s0, s0, 0x4000
	v_mov_b32_dpp v94, v194 row_shr:4 row_mask:0xf bank_mask:0x2
	s_addc_u32 s1, s1, 0
	s_nop 0
	v_mov_b32_dpp v94, v231 row_shr:8 row_mask:0xf bank_mask:0x4
	s_nop 0
	s_nop 0
	v_mov_b32_dpp v94, v232 row_shr:12 row_mask:0xf bank_mask:0x8
	v_mov_b32_e32 v95, v94
	s_nop 0
	s_nop 0
	v_permlane16_swap_b32_e32 v94, v95
	s_nop 0
	v_add_f32_e32 v96, v94, v95
	v_mov_b32_e32 v97, v96
	s_nop 0
	s_nop 0
	v_permlane32_swap_b32_e32 v96, v97
	s_nop 0
	v_add_f32_e32 v98, v96, v97
	s_nop 0
	v_readlane_b32 s24, v98, 0
	v_readlane_b32 s25, v98, 4
	v_readlane_b32 s26, v98, 8
	v_readlane_b32 s27, v98, 12
	v_writelane_b32 v82, s24, m0
	v_writelane_b32 v33, s25, m0
	v_writelane_b32 v0, s26, m0
	v_writelane_b32 v1, s27, m0
	s_cmp_eq_u32 s2, 36
	s_cbranch_scc0 .LBB0_69
; DEVI void phase_p7(const int TIDX, const int BIDX, const int GDIM, KAP KA, unsigned char* WSB, float* OUTB, int l, unsigned char* smem) {
;     ...
;       for (int t = 0; t < 4; ++t) {
;         const int tok = r4 * 4 + t;
;         float gl[4];
; #pragma unroll
;         for (int j = 0; j < 4; ++j) gl[j] = __shfl(mine[t], j);
;         int gi = 0; float gm = gl[0];
; #pragma unroll
;         for (int j = 1; j < 4; ++j) if (gl[j] > gm) { gm = gl[j]; gi = j; }
;         float gs = 0.f;
; #pragma unroll
;         for (int j = 0; j < 4; ++j) gs += expf(gl[j] - gm);
;         const float gtop = 1.f / gs;
;         float el[8];
; #pragma unroll
;         for (int j = 0; j < 8; ++j) el[j] = __shfl(mine[t], 4 + gi * 8 + j);
;         float em = el[0];
; #pragma unroll
;         for (int j = 1; j < 8; ++j) em = fmaxf(em, el[j]);
;         float pe[8], es = 0.f;
; #pragma unroll
;         for (int j = 0; j < 8; ++j) { pe[j] = expf(el[j] - em); es += pe[j]; }
	v_bfe_u32 v154, v45, 1, 2
	ds_bpermute_b32 v2, v85, v82
	ds_bpermute_b32 v3, v86, v82
	ds_bpermute_b32 v4, v87, v82
	ds_bpermute_b32 v5, v88, v82
	ds_bpermute_b32 v142, v85, v33
	ds_bpermute_b32 v143, v86, v33
	ds_bpermute_b32 v144, v87, v33
	ds_bpermute_b32 v145, v88, v33
	ds_bpermute_b32 v146, v85, v0
	ds_bpermute_b32 v147, v86, v0
	ds_bpermute_b32 v148, v87, v0
	ds_bpermute_b32 v149, v88, v0
	ds_bpermute_b32 v150, v85, v1
	ds_bpermute_b32 v151, v86, v1
	ds_bpermute_b32 v152, v87, v1
	ds_bpermute_b32 v153, v88, v1
	s_waitcnt lgkmcnt(0)
	v_cmp_eq_u32_e32 vcc, 1, v154
	s_nop 1
	v_cndmask_b32_e32 v2, v2, v142, vcc
	v_cndmask_b32_e32 v3, v3, v143, vcc
	v_cndmask_b32_e32 v4, v4, v144, vcc
	v_cndmask_b32_e32 v5, v5, v145, vcc
	v_cmp_eq_u32_e32 vcc, 2, v154
	s_nop 1
	v_cndmask_b32_e32 v2, v2, v146, vcc
	v_cndmask_b32_e32 v3, v3, v147, vcc
	v_cndmask_b32_e32 v4, v4, v148, vcc
	v_cndmask_b32_e32 v5, v5, v149, vcc
	v_cmp_eq_u32_e32 vcc, 3, v154
	s_nop 1
	v_cndmask_b32_e32 v2, v2, v150, vcc
	v_cndmask_b32_e32 v3, v3, v151, vcc
	v_cndmask_b32_e32 v4, v4, v152, vcc
	v_cndmask_b32_e32 v5, v5, v153, vcc
	s_waitcnt lgkmcnt(2)
	v_cmp_gt_f32_e32 vcc, v3, v2
	s_nop 1
	v_cndmask_b32_e32 v6, v2, v3, vcc
	s_waitcnt lgkmcnt(1)
	v_cmp_lt_f32_e64 s[22:23], v6, v4
	s_nop 1
	v_cndmask_b32_e64 v6, v6, v4, s[22:23]
	s_waitcnt lgkmcnt(0)
	v_cmp_lt_f32_e64 s[24:25], v6, v5
	s_nop 1
	v_cndmask_b32_e64 v6, v6, v5, s[24:25]
	v_sub_f32_e32 v7, v2, v6
	v_sub_f32_e32 v2, v3, v6
	v_mul_f32_e32 v3, 0x3fb8aa3b, v2
	v_fma_f32 v8, v2, s61, -v3
	v_rndne_f32_e32 v9, v3
	v_fmac_f32_e32 v8, 0x32a5705f, v2
	v_sub_f32_e32 v3, v3, v9
	v_add_f32_e32 v3, v3, v8
	v_exp_f32_e32 v3, v3
	v_cvt_i32_f32_e32 v8, v9
	v_cmp_ngt_f32_e64 s[26:27], s90, v2
	v_mul_f32_e32 v16, 0x3fb8aa3b, v7
	v_fma_f32 v17, v7, s61, -v16
	v_ldexp_f32 v3, v3, v8
	v_cndmask_b32_e64 v3, 0, v3, s[26:27]
	v_cmp_nlt_f32_e64 s[26:27], s91, v2
	v_sub_f32_e32 v2, v4, v6
	v_mul_f32_e32 v4, 0x3fb8aa3b, v2
	v_fma_f32 v8, v2, s61, -v4
	v_rndne_f32_e32 v9, v4
	v_fmac_f32_e32 v8, 0x32a5705f, v2
	v_sub_f32_e32 v4, v4, v9
	v_add_f32_e32 v4, v4, v8
	v_exp_f32_e32 v4, v4
	v_cvt_i32_f32_e32 v8, v9
	v_cndmask_b32_e64 v3, v229, v3, s[26:27]
	v_cmp_ngt_f32_e64 s[26:27], s90, v2
	v_rndne_f32_e32 v18, v16
	v_ldexp_f32 v4, v4, v8
	v_cndmask_b32_e64 v4, 0, v4, s[26:27]
	v_cmp_nlt_f32_e64 s[26:27], s91, v2
	v_sub_f32_e32 v2, v5, v6
	v_mul_f32_e32 v5, 0x3fb8aa3b, v2
	v_fma_f32 v6, v2, s61, -v5
	v_rndne_f32_e32 v8, v5
	v_fmac_f32_e32 v6, 0x32a5705f, v2
	v_sub_f32_e32 v5, v5, v8
	v_add_f32_e32 v5, v5, v6
	v_exp_f32_e32 v5, v5
	v_cvt_i32_f32_e32 v6, v8
	v_cndmask_b32_e64 v4, v229, v4, s[26:27]
	v_cmp_ngt_f32_e64 s[26:27], s90, v2
	v_fmac_f32_e32 v17, 0x32a5705f, v7
	v_ldexp_f32 v5, v5, v6
	v_cndmask_b32_e64 v5, 0, v5, s[26:27]
	v_cmp_nlt_f32_e64 s[26:27], s91, v2
	v_sub_f32_e32 v16, v16, v18
	v_add_f32_e32 v16, v16, v17
	v_cndmask_b32_e64 v6, v229, v5, s[26:27]
	v_cndmask_b32_e64 v5, 0, 8, vcc
	v_cndmask_b32_e64 v5, v5, 16, s[22:23]
	v_exp_f32_e32 v16, v16
	v_cvt_i32_f32_e32 v17, v18
	v_cndmask_b32_e64 v5, v5, 24, s[24:25]
	v_or_b32_e32 v8, v5, v84
	v_lshlrev_b32_e32 v8, 2, v8
	v_mov_b32_e32 v155, v8
	ds_bpermute_b32 v9, v8, v82
	ds_bpermute_b32 v10, v8, v82 offset:4
	v_ldexp_f32 v16, v16, v17
	v_cmp_ngt_f32_e32 vcc, s90, v7
	ds_bpermute_b32 v11, v8, v82 offset:8
	ds_bpermute_b32 v12, v8, v82 offset:12
	v_cndmask_b32_e32 v16, 0, v16, vcc
	v_cmp_nlt_f32_e32 vcc, s91, v7
	ds_bpermute_b32 v13, v8, v82 offset:16
	ds_bpermute_b32 v14, v8, v82 offset:20
	v_cndmask_b32_e32 v7, v229, v16, vcc
	v_add_f32_e32 v3, v7, v3
	ds_bpermute_b32 v15, v8, v82 offset:24
	ds_bpermute_b32 v8, v8, v82 offset:28
	ds_bpermute_b32 v156, v155, v33
	ds_bpermute_b32 v157, v155, v33 offset:4
	ds_bpermute_b32 v158, v155, v33 offset:8
	ds_bpermute_b32 v159, v155, v33 offset:12
	ds_bpermute_b32 v160, v155, v33 offset:16
	ds_bpermute_b32 v162, v155, v33 offset:20
	ds_bpermute_b32 v163, v155, v33 offset:24
	ds_bpermute_b32 v164, v155, v33 offset:28
	ds_bpermute_b32 v165, v155, v0
	ds_bpermute_b32 v166, v155, v0 offset:4
	ds_bpermute_b32 v167, v155, v0 offset:8
	ds_bpermute_b32 v168, v155, v0 offset:12
	ds_bpermute_b32 v169, v155, v0 offset:16
	ds_bpermute_b32 v170, v155, v0 offset:20
	ds_bpermute_b32 v171, v155, v0 offset:24
	ds_bpermute_b32 v172, v155, v0 offset:28
	ds_bpermute_b32 v173, v155, v1
	ds_bpermute_b32 v174, v155, v1 offset:4
	ds_bpermute_b32 v175, v155, v1 offset:8
	ds_bpermute_b32 v176, v155, v1 offset:12
	ds_bpermute_b32 v177, v155, v1 offset:16
	ds_bpermute_b32 v178, v155, v1 offset:20
	ds_bpermute_b32 v179, v155, v1 offset:24
	ds_bpermute_b32 v180, v155, v1 offset:28
	v_add_f32_e32 v3, v4, v3
	v_add_f32_e32 v3, v6, v3
	s_waitcnt lgkmcnt(0)
	v_cmp_eq_u32_e32 vcc, 1, v154
	s_nop 1
	v_cndmask_b32_e32 v9, v9, v156, vcc
	v_cndmask_b32_e32 v10, v10, v157, vcc
	v_cndmask_b32_e32 v11, v11, v158, vcc
	v_cndmask_b32_e32 v12, v12, v159, vcc
	v_cndmask_b32_e32 v13, v13, v160, vcc
	v_cndmask_b32_e32 v14, v14, v162, vcc
	v_cndmask_b32_e32 v15, v15, v163, vcc
	v_cndmask_b32_e32 v8, v8, v164, vcc
	v_cmp_eq_u32_e32 vcc, 2, v154
	s_nop 1
	v_cndmask_b32_e32 v9, v9, v165, vcc
	v_cndmask_b32_e32 v10, v10, v166, vcc
	v_cndmask_b32_e32 v11, v11, v167, vcc
	v_cndmask_b32_e32 v12, v12, v168, vcc
	v_cndmask_b32_e32 v13, v13, v169, vcc
	v_cndmask_b32_e32 v14, v14, v170, vcc
	v_cndmask_b32_e32 v15, v15, v171, vcc
	v_cndmask_b32_e32 v8, v8, v172, vcc
	v_cmp_eq_u32_e32 vcc, 3, v154
	s_nop 1
	v_cndmask_b32_e32 v9, v9, v173, vcc
	v_cndmask_b32_e32 v10, v10, v174, vcc
	v_cndmask_b32_e32 v11, v11, v175, vcc
	v_cndmask_b32_e32 v12, v12, v176, vcc
	v_cndmask_b32_e32 v13, v13, v177, vcc
	v_cndmask_b32_e32 v14, v14, v178, vcc
	v_cndmask_b32_e32 v15, v15, v179, vcc
	v_cndmask_b32_e32 v8, v8, v180, vcc
	s_waitcnt lgkmcnt(6)
; DEVI void phase_p7(const int TIDX, const int BIDX, const int GDIM, KAP KA, unsigned char* WSB, float* OUTB, int l, unsigned char* smem) {
;     ...
;         float em = el[0];
; #pragma unroll
;         for (int j = 1; j < 8; ++j) em = fmaxf(em, el[j]);
;         float pe[8], es = 0.f;
; #pragma unroll
;         for (int j = 0; j < 8; ++j) { pe[j] = expf(el[j] - em); es += pe[j]; }
; #pragma unroll
;         for (int j = 0; j < 8; ++j) pe[j] = pe[j] / es;
	v_max_f32_e32 v4, v10, v10
	v_max_f32_e32 v6, v9, v9
	v_max_f32_e32 v4, v6, v4
	s_waitcnt lgkmcnt(4)
	v_max3_f32 v4, v4, v11, v12
	s_waitcnt lgkmcnt(2)
	v_max3_f32 v4, v4, v13, v14
	s_waitcnt lgkmcnt(0)
	v_max3_f32 v4, v4, v15, v8
	v_sub_f32_e32 v6, v9, v4
	v_mul_f32_e32 v7, 0x3fb8aa3b, v6
	v_fma_f32 v9, v6, s61, -v7
	v_rndne_f32_e32 v16, v7
	v_fmac_f32_e32 v9, 0x32a5705f, v6
	v_sub_f32_e32 v7, v7, v16
	v_add_f32_e32 v7, v7, v9
	v_exp_f32_e32 v7, v7
	v_cvt_i32_f32_e32 v9, v16
	v_cmp_ngt_f32_e32 vcc, s90, v6
	v_mov_b32_e32 v2, 0
	v_ldexp_f32 v7, v7, v9
	v_cndmask_b32_e32 v7, 0, v7, vcc
	v_cmp_nlt_f32_e32 vcc, s91, v6
	s_nop 1
	v_cndmask_b32_e32 v6, v229, v7, vcc
	v_sub_f32_e32 v7, v10, v4
	v_mul_f32_e32 v9, 0x3fb8aa3b, v7
	v_fma_f32 v10, v7, s61, -v9
	v_rndne_f32_e32 v16, v9
	v_fmac_f32_e32 v10, 0x32a5705f, v7
	v_sub_f32_e32 v9, v9, v16
	v_add_f32_e32 v9, v9, v10
	v_exp_f32_e32 v9, v9
	v_cvt_i32_f32_e32 v10, v16
	v_cmp_ngt_f32_e32 vcc, s90, v7
	v_ldexp_f32 v9, v9, v10
	v_sub_f32_e32 v10, v11, v4
	v_mul_f32_e32 v11, 0x3fb8aa3b, v10
	v_fma_f32 v16, v10, s61, -v11
	v_rndne_f32_e32 v17, v11
	v_fmac_f32_e32 v16, 0x32a5705f, v10
	v_sub_f32_e32 v11, v11, v17
	v_add_f32_e32 v11, v11, v16
	v_exp_f32_e32 v11, v11
	v_cvt_i32_f32_e32 v16, v17
	v_cndmask_b32_e32 v9, 0, v9, vcc
	v_cmp_nlt_f32_e32 vcc, s91, v7
	v_ldexp_f32 v11, v11, v16
	s_nop 0
	v_cndmask_b32_e32 v7, v229, v9, vcc
	v_cmp_ngt_f32_e32 vcc, s90, v10
	v_add_f32_e32 v9, v6, v7
	s_nop 0
	v_cndmask_b32_e32 v11, 0, v11, vcc
	v_cmp_nlt_f32_e32 vcc, s91, v10
	s_nop 1
	v_cndmask_b32_e32 v10, v229, v11, vcc
	v_sub_f32_e32 v11, v12, v4
	v_mul_f32_e32 v12, 0x3fb8aa3b, v11
	v_fma_f32 v16, v11, s61, -v12
	v_rndne_f32_e32 v17, v12
	v_fmac_f32_e32 v16, 0x32a5705f, v11
	v_sub_f32_e32 v12, v12, v17
	v_add_f32_e32 v12, v12, v16
	v_exp_f32_e32 v12, v12
	v_cvt_i32_f32_e32 v16, v17
	v_cmp_ngt_f32_e32 vcc, s90, v11
	v_add_f32_e32 v9, v10, v9
	v_ldexp_f32 v12, v12, v16
	v_cndmask_b32_e32 v12, 0, v12, vcc
	v_cmp_nlt_f32_e32 vcc, s91, v11
	s_nop 1
	v_cndmask_b32_e32 v11, v229, v12, vcc
	v_sub_f32_e32 v12, v13, v4
	v_mul_f32_e32 v13, 0x3fb8aa3b, v12
	v_fma_f32 v16, v12, s61, -v13
	v_rndne_f32_e32 v17, v13
	v_fmac_f32_e32 v16, 0x32a5705f, v12
	v_sub_f32_e32 v13, v13, v17
	v_add_f32_e32 v13, v13, v16
	v_exp_f32_e32 v13, v13
	v_cvt_i32_f32_e32 v16, v17
	v_cmp_ngt_f32_e32 vcc, s90, v12
	v_add_f32_e32 v9, v11, v9
	v_ldexp_f32 v13, v13, v16
	v_cndmask_b32_e32 v13, 0, v13, vcc
	v_cmp_nlt_f32_e32 vcc, s91, v12
	s_nop 1
	v_cndmask_b32_e32 v12, v229, v13, vcc
	v_sub_f32_e32 v13, v14, v4
	v_mul_f32_e32 v14, 0x3fb8aa3b, v13
	v_fma_f32 v16, v13, s61, -v14
	v_rndne_f32_e32 v17, v14
	v_fmac_f32_e32 v16, 0x32a5705f, v13
	v_sub_f32_e32 v14, v14, v17
	v_add_f32_e32 v14, v14, v16
	v_exp_f32_e32 v14, v14
	v_cvt_i32_f32_e32 v16, v17
	v_cmp_ngt_f32_e32 vcc, s90, v13
	v_add_f32_e32 v9, v12, v9
	v_ldexp_f32 v14, v14, v16
	v_cndmask_b32_e32 v14, 0, v14, vcc
	v_cmp_nlt_f32_e32 vcc, s91, v13
	s_nop 1
	v_cndmask_b32_e32 v13, v229, v14, vcc
	v_sub_f32_e32 v14, v15, v4
	v_mul_f32_e32 v15, 0x3fb8aa3b, v14
	v_fma_f32 v16, v14, s61, -v15
	v_rndne_f32_e32 v17, v15
	v_fmac_f32_e32 v16, 0x32a5705f, v14
	v_sub_f32_e32 v15, v15, v17
	v_add_f32_e32 v15, v15, v16
	v_exp_f32_e32 v15, v15
	v_cvt_i32_f32_e32 v16, v17
	v_cmp_ngt_f32_e32 vcc, s90, v14
	v_sub_f32_e32 v4, v8, v4
	v_mul_f32_e32 v8, 0x3fb8aa3b, v4
	v_ldexp_f32 v15, v15, v16
	v_cndmask_b32_e32 v15, 0, v15, vcc
	v_cmp_nlt_f32_e32 vcc, s91, v14
	v_rndne_f32_e32 v16, v8
	v_add_f32_e32 v9, v13, v9
	v_cndmask_b32_e32 v14, v229, v15, vcc
	v_fma_f32 v15, v4, s61, -v8
	v_fmac_f32_e32 v15, 0x32a5705f, v4
	v_sub_f32_e32 v8, v8, v16
	v_add_f32_e32 v8, v8, v15
	v_exp_f32_e32 v8, v8
	v_cvt_i32_f32_e32 v15, v16
	v_cmp_ngt_f32_e32 vcc, s90, v4
	v_add_f32_e32 v9, v14, v9
	v_ldexp_f32 v8, v8, v15
	v_cndmask_b32_e32 v8, 0, v8, vcc
	v_cmp_nlt_f32_e32 vcc, s91, v4
	s_nop 1
	v_cndmask_b32_e32 v4, v229, v8, vcc
	v_add_f32_e32 v8, v4, v9
	v_div_scale_f32 v9, s[0:1], v8, v8, v6
	v_rcp_f32_e32 v15, v9
	s_nop 0
	v_fma_f32 v16, -v9, v15, 1.0
	v_fmac_f32_e32 v15, v16, v15
	v_div_scale_f32 v16, vcc, v6, v8, v6
	v_mul_f32_e32 v17, v16, v15
	v_fma_f32 v18, -v9, v17, v16
	v_fmac_f32_e32 v17, v18, v15
	v_fma_f32 v9, -v9, v17, v16
	v_div_fmas_f32 v9, v9, v15, v17
	v_div_fixup_f32 v6, v9, v8, v6
	v_div_scale_f32 v9, s[0:1], v8, v8, v7
	v_rcp_f32_e32 v15, v9
	v_cmp_nlt_f32_e64 s[24:25], -1.0, v6
	v_fma_f32 v16, -v9, v15, 1.0
	v_fmac_f32_e32 v15, v16, v15
	v_div_scale_f32 v16, vcc, v7, v8, v7
	v_mul_f32_e32 v17, v16, v15
	v_fma_f32 v18, -v9, v17, v16
	v_fmac_f32_e32 v17, v18, v15
	v_fma_f32 v9, -v9, v17, v16
	v_div_fmas_f32 v9, v9, v15, v17
	v_div_fixup_f32 v9, v9, v8, v7
	v_div_scale_f32 v7, s[0:1], v8, v8, v10
	v_rcp_f32_e32 v15, v7
	s_nop 0
	v_fma_f32 v16, -v7, v15, 1.0
	v_fmac_f32_e32 v15, v16, v15
	v_div_scale_f32 v16, vcc, v10, v8, v10
	v_mul_f32_e32 v17, v16, v15
; DEVI void phase_p7(const int TIDX, const int BIDX, const int GDIM, KAP KA, unsigned char* WSB, float* OUTB, int l, unsigned char* smem) {
;     ...
;         for (int j = 0; j < 8; ++j) pe[j] = pe[j] / es;
;         int i1 = 0; float p1 = pe[0];
; #pragma unroll
;         for (int j = 1; j < 8; ++j) if (pe[j] > p1) { p1 = pe[j]; i1 = j; }
;         int i2 = -1; float p2 = -1.f;
; #pragma unroll
;         for (int j = 0; j < 8; ++j) if (j != i1 && pe[j] > p2) { p2 = pe[j]; i2 = j; }
;         const float den = p1 + p2;
;         if (lane == 2 * t) { my_e = gi * 8 + i1; my_w = gtop * (p1 / den); my_tk = tok * 2; }
;         if (lane == 2 * t + 1) { my_e = gi * 8 + i2; my_w = gtop * (p2 / den); my_tk = tok * 2 + 1; }
	v_fma_f32 v18, -v7, v17, v16
	v_fmac_f32_e32 v17, v18, v15
	v_fma_f32 v7, -v7, v17, v16
	v_div_fmas_f32 v7, v7, v15, v17
	v_div_fixup_f32 v10, v7, v8, v10
	v_div_scale_f32 v7, s[0:1], v8, v8, v11
	v_rcp_f32_e32 v15, v7
	s_nop 0
	v_fma_f32 v16, -v7, v15, 1.0
	v_fmac_f32_e32 v15, v16, v15
	v_div_scale_f32 v16, vcc, v11, v8, v11
	v_mul_f32_e32 v17, v16, v15
	v_fma_f32 v18, -v7, v17, v16
	v_fmac_f32_e32 v17, v18, v15
	v_fma_f32 v7, -v7, v17, v16
	v_div_fmas_f32 v7, v7, v15, v17
	v_div_fixup_f32 v11, v7, v8, v11
	v_div_scale_f32 v7, s[0:1], v8, v8, v12
	v_rcp_f32_e32 v15, v7
	s_nop 0
	v_fma_f32 v16, -v7, v15, 1.0
	v_fmac_f32_e32 v15, v16, v15
	v_div_scale_f32 v16, vcc, v12, v8, v12
	v_mul_f32_e32 v17, v16, v15
	v_fma_f32 v18, -v7, v17, v16
	v_fmac_f32_e32 v17, v18, v15
	v_fma_f32 v7, -v7, v17, v16
	v_div_fmas_f32 v7, v7, v15, v17
	v_div_fixup_f32 v12, v7, v8, v12
	v_div_scale_f32 v7, s[0:1], v8, v8, v13
	v_rcp_f32_e32 v15, v7
	s_nop 0
	v_fma_f32 v16, -v7, v15, 1.0
	v_fmac_f32_e32 v15, v16, v15
	v_div_scale_f32 v16, vcc, v13, v8, v13
	v_mul_f32_e32 v17, v16, v15
	v_fma_f32 v18, -v7, v17, v16
	v_fmac_f32_e32 v17, v18, v15
	v_fma_f32 v7, -v7, v17, v16
	v_div_fmas_f32 v7, v7, v15, v17
	v_div_fixup_f32 v13, v7, v8, v13
	v_div_scale_f32 v7, s[0:1], v8, v8, v14
	v_rcp_f32_e32 v15, v7
	s_nop 0
	v_fma_f32 v16, -v7, v15, 1.0
	v_fmac_f32_e32 v15, v16, v15
	v_div_scale_f32 v16, vcc, v14, v8, v14
	v_mul_f32_e32 v17, v16, v15
	v_fma_f32 v18, -v7, v17, v16
	v_fmac_f32_e32 v17, v18, v15
	v_fma_f32 v7, -v7, v17, v16
	v_div_fmas_f32 v7, v7, v15, v17
	v_div_fixup_f32 v14, v7, v8, v14
	v_div_scale_f32 v7, s[0:1], v8, v8, v4
	v_rcp_f32_e32 v15, v7
	s_nop 0
	v_fma_f32 v16, -v7, v15, 1.0
	v_fmac_f32_e32 v15, v16, v15
	v_div_scale_f32 v16, vcc, v4, v8, v4
	v_mul_f32_e32 v17, v16, v15
	v_fma_f32 v18, -v7, v17, v16
	v_fmac_f32_e32 v17, v18, v15
	v_fma_f32 v7, -v7, v17, v16
	v_div_fmas_f32 v7, v7, v15, v17
	v_cmp_gt_f32_e32 vcc, v9, v6
	v_div_fixup_f32 v4, v7, v8, v4
	s_nop 0
	v_cndmask_b32_e32 v8, v6, v9, vcc
	v_cndmask_b32_e64 v7, 0, 1, vcc
	v_cmp_gt_f32_e32 vcc, v10, v8
	s_nop 1
	v_cndmask_b32_e32 v8, v8, v10, vcc
	v_cndmask_b32_e64 v7, v7, 2, vcc
	v_cmp_gt_f32_e32 vcc, v11, v8
	s_nop 1
	v_cndmask_b32_e32 v8, v8, v11, vcc
	v_cndmask_b32_e64 v7, v7, 3, vcc
	v_cmp_gt_f32_e32 vcc, v12, v8
	s_nop 1
	v_cndmask_b32_e32 v8, v8, v12, vcc
	v_cndmask_b32_e64 v7, v7, 4, vcc
	v_cmp_gt_f32_e32 vcc, v13, v8
	s_nop 1
	v_cndmask_b32_e32 v8, v8, v13, vcc
	v_cndmask_b32_e64 v7, v7, 5, vcc
	v_cmp_gt_f32_e32 vcc, v14, v8
	s_nop 1
	v_cndmask_b32_e32 v15, v8, v14, vcc
	v_cndmask_b32_e64 v7, v7, 6, vcc
	v_cmp_ngt_f32_e64 s[36:37], v4, v15
	s_and_b64 s[2:3], vcc, s[36:37]
	s_nop 0
	v_cndmask_b32_e64 v8, 7, v7, s[36:37]
	v_cmp_eq_u32_e64 s[22:23], 0, v8
	s_or_b64 s[0:1], s[24:25], s[22:23]
	v_cndmask_b32_e64 v6, v6, -1.0, s[0:1]
	v_cmp_ne_u32_e64 s[22:23], 1, v8
	v_cmp_gt_f32_e64 s[24:25], v9, v6
	s_and_b64 s[22:23], s[22:23], s[24:25]
	v_cndmask_b32_e64 v6, v6, v9, s[22:23]
	v_cmp_ne_u32_e64 s[24:25], 2, v8
	v_cmp_gt_f32_e64 s[26:27], v10, v6
	s_and_b64 s[24:25], s[24:25], s[26:27]
	v_cndmask_b32_e64 v6, v6, v10, s[24:25]
	v_cmp_ne_u32_e64 s[26:27], 3, v8
	v_cmp_gt_f32_e64 s[28:29], v11, v6
	s_and_b64 s[26:27], s[26:27], s[28:29]
	v_cndmask_b32_e64 v6, v6, v11, s[26:27]
	v_cmp_ne_u32_e64 s[28:29], 4, v8
	v_cmp_gt_f32_e64 s[30:31], v12, v6
	s_and_b64 s[28:29], s[28:29], s[30:31]
	v_cndmask_b32_e64 v6, v6, v12, s[28:29]
	v_cmp_ne_u32_e64 s[30:31], 5, v8
	v_cmp_gt_f32_e64 s[34:35], v13, v6
	s_and_b64 s[34:35], s[30:31], s[34:35]
	v_cndmask_b32_e64 v7, v4, v15, s[36:37]
	v_cndmask_b32_e64 v6, v6, v13, s[34:35]
	v_cmp_ngt_f32_e32 vcc, v14, v6
	s_or_b64 s[30:31], s[2:3], vcc
	v_cndmask_b32_e64 v6, v14, v6, s[30:31]
	v_cmp_gt_f32_e32 vcc, v4, v6
	s_and_b64 s[36:37], s[36:37], vcc
	v_cndmask_b32_e64 v6, v6, v4, s[36:37]
	v_div_scale_f32 v4, s[2:3], v3, v3, 1.0
	v_rcp_f32_e32 v9, v4
	s_nop 0
	v_fma_f32 v10, -v4, v9, 1.0
	v_fmac_f32_e32 v9, v10, v9
	v_div_scale_f32 v10, vcc, 1.0, v3, 1.0
	v_mul_f32_e32 v11, v10, v9
	v_fma_f32 v12, -v4, v11, v10
	v_fmac_f32_e32 v11, v12, v9
	v_fma_f32 v4, -v4, v11, v10
	v_div_fmas_f32 v4, v4, v9, v11
	v_div_fixup_f32 v9, v4, v3, 1.0
	v_add_f32_e32 v10, v7, v6
	v_mov_b32_e32 v4, 0
	v_mov_b32_e32 v3, 0
	s_or_b64 s[62:63], s[6:7], s[10:11]
	s_or_b64 s[62:63], s[62:63], s[14:15]
	s_or_b64 s[62:63], s[62:63], s[18:19]
	s_and_saveexec_b64 s[2:3], s[62:63]
	s_cbranch_execz .LBB0_72
	v_div_scale_f32 v2, s[62:63], v10, v10, v7
	v_rcp_f32_e32 v4, v2
	v_add_u32_e32 v3, v8, v5
	v_fma_f32 v8, -v2, v4, 1.0
	v_fmac_f32_e32 v4, v8, v4
	v_div_scale_f32 v8, vcc, v7, v10, v7
	v_mul_f32_e32 v11, v8, v4
	v_fma_f32 v12, -v2, v11, v8
	v_fmac_f32_e32 v11, v12, v4
	v_fma_f32 v2, -v2, v11, v8
	v_div_fmas_f32 v2, v2, v4, v11
	v_div_fixup_f32 v2, v2, v10, v7
	v_mul_f32_e32 v4, v9, v2
	v_lshl_or_b32 v2, v32, 3, v45
